# scan items assigned XCD-contiguously (the four quarter-workgroups of a head share one L2)
# speedup vs baseline: 1.0092x; 1.0026x over previous
.LBB0_1228:
	s_cmp_lt_i32 s30, 8
	s_cselect_b64 s[8:9], -1, 0
	s_and_b64 s[16:17], s[8:9], s[6:7]
	s_andn2_b64 vcc, exec, s[16:17]
	s_cbranch_vccnz .LBB0_1247
	s_cmpk_gt_i32 s2, 0xff
	v_readfirstlane_b32 s6, v231
	s_cbranch_scc1 .LBB0_1247
	s_load_dwordx4 s[8:11], s[0:1], 0x168
	v_bfe_u32 v2, v231, 4, 2
	s_load_dwordx2 s[18:19], s[0:1], 0x70
	s_load_dwordx4 s[12:15], s[0:1], 0xa0
	v_lshlrev_b32_e32 v0, 2, v232
	v_lshl_add_u32 v1, v136, 2, 0
	s_waitcnt lgkmcnt(0)
	s_add_u32 s20, s10, 0x1d300000
	s_addc_u32 s21, s11, 0
	s_add_u32 s22, s10, 0x16800000
	s_addc_u32 s23, s11, 0
	s_add_u32 s24, s10, 0x1f380000
	s_addc_u32 s25, s11, 0
	s_add_u32 s3, s8, 0x4185200
	s_addc_u32 s46, s9, 0
	s_lshr_b32 s7, s6, 6
	s_lshr_b32 s8, s6, 4
	s_cmpk_gt_u32 s6, 0xff
	v_and_or_b32 v33, s8, 12, v2
	s_cselect_b64 s[8:9], -1, 0
	s_add_i32 s36, s7, -4
	s_lshl_b32 s47, s36, 3
	s_and_b32 s37, s47, 0x7f8
	s_cmp_lg_u32 s37, 0
	s_cselect_b64 s[26:27], -1, 0
	s_cmp_eq_u32 s37, 0
	v_cndmask_b32_e64 v2, 0, -1, s[26:27]
	s_cselect_b64 s[26:27], -1, 0
	s_lshl_b32 s59, s36, 11
	v_readfirstlane_b32 s58, v2
	s_cmpk_lt_u32 s6, 0x100
	v_cndmask_b32_e64 v2, 0, 1, s[8:9]
	v_lshlrev_b32_e32 v32, 4, v232
	v_mov_b32_e32 v9, 0
	s_cselect_b64 s[36:37], -1, 0
	s_lshl_b32 s60, s7, 3
	s_and_b32 s86, s2, 7
	s_lshl_b32 s86, s86, 5
	s_lshr_b32 s61, s2, 3
	s_add_i32 s86, s86, s61
	s_lshl_b32 s61, s86, 5
	s_lshl_b32 s62, s34, 5
	s_lshl_b32 s63, s86, 4
	s_lshl_b32 s64, s34, 4
	s_movk_i32 s65, 0x2000
	v_cmp_ne_u32_e64 s[6:7], 1, v2
	v_add_u32_e32 v34, s59, v1
	s_add_i32 s66, 0, 0xc000
	s_add_i32 s67, 0, 0x10000
	s_add_i32 s68, 0, 0x4000
	s_mov_b32 s69, 0x23501000
	s_mov_b32 s70, 0x23503000
	s_mov_b32 s71, 0x23505000
	s_mov_b32 s72, 0x23507000
	s_mov_b32 s73, 0x23509000
	s_mov_b32 s74, 0x2350b000
	s_mov_b32 s75, 0x2350d000
	s_mov_b32 s76, 0x2350f000
	s_mov_b32 s77, 0x23511000
	s_mov_b32 s78, 0x23513000
	s_mov_b32 s79, 0x23515000
	s_mov_b32 s80, 0x23517000
	s_mov_b32 s81, 0x23519000
	s_mov_b32 s83, 0x2351b000
	s_mov_b32 s84, 0x2351d000
	s_mov_b32 s85, 0x2351e000
	v_lshlrev_b32_e32 v10, 2, v0
	v_mov_b32_e32 v35, 0x3480
	s_branch .LBB0_1232
